# v4 + K2 tile LDS-DMA issued at pass start (before Q loads) in diff attention
# baseline (speedup 1.0000x reference)
.LBB0_490:
	s_mov_b64 s[2:3], s[62:63]
	s_add_u32 s4, s2, s14
	s_addc_u32 s13, s3, s15
	s_lshl_b32 s12, s5, 6
	s_or_b32 s72, s12, s35
	s_lshl_b64 s[10:11], s[72:73], 1
	s_add_u32 s24, s4, s10
	s_addc_u32 s25, s13, s11
	v_lshl_add_u64 v[4:5], s[2:3], 0, v[214:215]
	v_lshl_add_u64 v[6:7], s[2:3], 0, v[216:217]
	s_lshl_b32 s72, s35, 1
	v_lshl_add_u64 v[4:5], v[4:5], 0, s[10:11]
	v_lshl_add_u64 v[6:7], v[6:7], 0, s[72:73]
	v_lshl_add_u64 v[4:5], s[16:17], 1, v[4:5]
	s_mov_b64 s[10:11], 0x8000000
	v_lshl_add_u64 v[6:7], s[18:19], 1, v[6:7]
	s_waitcnt lgkmcnt(0)
	s_barrier
	s_cmp_lg_u32 0, -1
	v_lshl_add_u64 v[36:37], v[4:5], 0, s[10:11]
	v_lshl_add_u64 v[6:7], v[6:7], 0, v[2:3]
	s_mov_b64 s[10:11], 0x10000000
	s_mov_b32 s4, m0
	s_mov_b32 m0, s31
	s_nop 0
	global_load_lds_dwordx4 v[36:37], off
	s_mov_b32 m0, s4
	s_cselect_b32 s13, 0, 0
	v_lshl_add_u64 v[38:39], v[6:7], 0, s[10:11]
	s_mov_b32 s4, m0
	s_mov_b32 m0, s34
	s_nop 0
	global_load_lds_dwordx4 v[38:39], off
	s_mov_b32 m0, s4
	s_mov_b64 s[10:11], 0x10000080
	s_add_i32 s13, s13, s30
	v_lshl_add_u64 v[6:7], v[6:7], 0, s[10:11]
	s_add_i32 s4, s13, 0x8000
	s_mov_b32 s10, m0
	s_mov_b32 m0, s4
	s_nop 0
	global_load_lds_dwordx4 v[6:7], off
	s_mov_b32 m0, s10
	s_mov_b64 s[10:11], 0x8008000
	v_lshl_add_u64 v[6:7], v[4:5], 0, s[10:11]
	v_mov_b32_e32 v229, v3
	s_add_i32 s4, s13, 0x2000
	s_mov_b32 s10, m0
	s_mov_b32 m0, s4
	s_nop 0
	global_load_lds_dwordx4 v[6:7], off
	s_mov_b32 m0, s10
	s_mov_b64 s[10:11], 0x8010000
	v_lshl_add_u64 v[8:9], v[4:5], 0, s[10:11]
	s_add_i32 m0, s13, 0x4000
	s_nop 0
	global_load_lds_dwordx4 v[8:9], off
	v_lshl_add_u64 v[6:7], s[24:25], 0, v[228:229]
	v_mov_b32_e32 v231, v3
	v_lshl_add_u64 v[6:7], v[6:7], 0, v[230:231]
	global_load_dwordx4 v[160:163], v[6:7], off
	global_load_dwordx4 v[156:159], v[6:7], off offset:32
	global_load_dwordx4 v[152:155], v[6:7], off offset:64
	global_load_dwordx4 v[148:151], v[6:7], off offset:96
	s_or_b32 s4, s5, s36
	s_lshl_b32 s4, s4, 1
	s_ashr_i32 s5, s4, 31
	s_lshl_b64 s[4:5], s[4:5], 2
	s_add_u32 s4, s64, s4
	s_addc_u32 s5, s65, s5
	global_load_dwordx2 v[10:11], v3, s[4:5]
	s_mov_b32 s4, 0x3f828f5c
	s_addk_i32 s13, 0x4000
	s_waitcnt vmcnt(0)
	v_and_b32_e32 v7, 0xffff0000, v160
	v_lshlrev_b32_e32 v6, 16, v160
	v_mul_f32_e32 v8, v7, v7
	v_fmac_f32_e32 v8, v6, v6
	v_lshlrev_b32_e32 v6, 16, v161
	v_fmac_f32_e32 v8, v6, v6
	v_and_b32_e32 v6, 0xffff0000, v161
	v_fmac_f32_e32 v8, v6, v6
	v_lshlrev_b32_e32 v6, 16, v162
	v_fmac_f32_e32 v8, v6, v6
	v_and_b32_e32 v6, 0xffff0000, v162
	v_fmac_f32_e32 v8, v6, v6
	v_lshlrev_b32_e32 v6, 16, v163
	v_fmac_f32_e32 v8, v6, v6
	v_and_b32_e32 v6, 0xffff0000, v163
	v_fmac_f32_e32 v8, v6, v6
	v_lshlrev_b32_e32 v6, 16, v156
	v_fmac_f32_e32 v8, v6, v6
	v_and_b32_e32 v6, 0xffff0000, v156
	v_fmac_f32_e32 v8, v6, v6
	v_lshlrev_b32_e32 v6, 16, v157
	v_fmac_f32_e32 v8, v6, v6
	v_and_b32_e32 v6, 0xffff0000, v157
	v_fmac_f32_e32 v8, v6, v6
	v_lshlrev_b32_e32 v6, 16, v158
	v_fmac_f32_e32 v8, v6, v6
	v_and_b32_e32 v6, 0xffff0000, v158
	v_fmac_f32_e32 v8, v6, v6
	v_lshlrev_b32_e32 v6, 16, v159
	v_fmac_f32_e32 v8, v6, v6
	v_and_b32_e32 v6, 0xffff0000, v159
	v_fmac_f32_e32 v8, v6, v6
	v_lshlrev_b32_e32 v6, 16, v152
	v_fmac_f32_e32 v8, v6, v6
	v_and_b32_e32 v6, 0xffff0000, v152
	v_fmac_f32_e32 v8, v6, v6
	v_lshlrev_b32_e32 v6, 16, v153
	v_fmac_f32_e32 v8, v6, v6
	v_and_b32_e32 v6, 0xffff0000, v153
	v_fmac_f32_e32 v8, v6, v6
	v_lshlrev_b32_e32 v6, 16, v154
	v_fmac_f32_e32 v8, v6, v6
	v_and_b32_e32 v6, 0xffff0000, v154
	v_fmac_f32_e32 v8, v6, v6
	v_lshlrev_b32_e32 v6, 16, v155
	v_fmac_f32_e32 v8, v6, v6
	v_and_b32_e32 v6, 0xffff0000, v155
	v_fmac_f32_e32 v8, v6, v6
	v_and_b32_e32 v7, 0xffff0000, v148
	v_lshlrev_b32_e32 v6, 16, v148
	v_pk_mul_f32 v[6:7], v[6:7], v[6:7]
	v_mov_b32_e32 v9, v11
	v_add_f32_e32 v6, v6, v8
	v_add_f32_e32 v8, v7, v6
	v_and_b32_e32 v7, 0xffff0000, v149
	v_lshlrev_b32_e32 v6, 16, v149
	v_pk_mul_f32 v[6:7], v[6:7], v[6:7]
	s_nop 0
	v_add_f32_e32 v6, v6, v8
	v_add_f32_e32 v8, v7, v6
	v_and_b32_e32 v7, 0xffff0000, v150
	v_lshlrev_b32_e32 v6, 16, v150
	v_pk_mul_f32 v[6:7], v[6:7], v[6:7]
	s_nop 0
	v_add_f32_e32 v6, v6, v8
	v_add_f32_e32 v8, v7, v6
	v_and_b32_e32 v7, 0xffff0000, v151
	v_lshlrev_b32_e32 v6, 16, v151
	v_pk_mul_f32 v[6:7], v[6:7], v[6:7]
	s_nop 0
	v_add_f32_e32 v6, v6, v8
	v_add_f32_e32 v6, v7, v6
	v_mov_b32_e32 v8, v6
	s_nop 1
	v_permlane32_swap_b32_e32 v6, v8
	v_mov_b32_e32 v7, v10
	v_pk_add_f32 v[6:7], v[6:7], v[8:9]
	s_nop 0
	v_mul_f32_e32 v6, v6, v7
	v_cmp_gt_f32_e32 vcc, s46, v6
	v_mul_f32_e32 v7, 0x4f800000, v6
	s_nop 0
	v_cndmask_b32_e32 v6, v6, v7, vcc
	v_sqrt_f32_e32 v7, v6
	s_nop 0
	v_add_u32_e32 v8, -1, v7
	v_fma_f32 v9, -v8, v7, v6
	v_cmp_ge_f32_e64 s[10:11], 0, v9
	v_add_u32_e32 v9, 1, v7
	s_nop 0
	v_cndmask_b32_e64 v8, v7, v8, s[10:11]
	v_fma_f32 v7, -v9, v7, v6
	v_cmp_lt_f32_e64 s[10:11], 0, v7
	s_nop 1
	v_cndmask_b32_e64 v7, v8, v9, s[10:11]
	v_mul_f32_e32 v8, 0x37800000, v7
	v_cndmask_b32_e32 v7, v7, v8, vcc
	v_cmp_class_f32_e32 vcc, v6, v244
	s_nop 1
	v_cndmask_b32_e32 v6, v7, v6, vcc
	v_fma_f32 v6, v6, s4, 1.0
	s_mov_b32 s4, 0x42700000
	v_cmp_lt_f32_e32 vcc, s4, v6
	s_waitcnt vmcnt(3) lgkmcnt(0)
	s_barrier
	ds_read_b128 v[4:7], v251
	ds_read_b128 v[20:23], v251 offset:512
	s_waitcnt lgkmcnt(1)
	v_mfma_f32_32x32x16_bf16 v[4:19], v[4:7], v[160:163], 0
	ds_read_b128 v[40:43], v251 offset:2048
	ds_read_b128 v[44:47], v251 offset:2560
	s_cmp_lg_u64 vcc, 0
	s_cselect_b64 s[4:5], -1, 0
	s_waitcnt lgkmcnt(2)
	v_mfma_f32_32x32x16_bf16 v[20:35], v[20:23], v[160:163], 0
	s_waitcnt lgkmcnt(1)
	v_mfma_f32_32x32x16_bf16 v[4:19], v[40:43], v[156:159], v[4:19]
	s_waitcnt lgkmcnt(0)
	v_mfma_f32_32x32x16_bf16 v[20:35], v[44:47], v[156:159], v[20:35]
	ds_read_b128 v[40:43], v251 offset:4096
	ds_read_b128 v[44:47], v251 offset:4608
	s_waitcnt lgkmcnt(1)
	v_mfma_f32_32x32x16_bf16 v[4:19], v[40:43], v[152:155], v[4:19]
	s_waitcnt lgkmcnt(0)
	v_mfma_f32_32x32x16_bf16 v[20:35], v[44:47], v[152:155], v[20:35]
	ds_read_b128 v[40:43], v251 offset:6144
	ds_read_b128 v[44:47], v251 offset:6656
	s_waitcnt lgkmcnt(1)
	v_mfma_f32_32x32x16_bf16 v[4:19], v[40:43], v[148:151], v[4:19]
	s_waitcnt lgkmcnt(0)
	v_mfma_f32_32x32x16_bf16 v[20:35], v[44:47], v[148:151], v[20:35]
	s_cbranch_vccz .LBB0_578
	s_nop 8
	v_max_f32_e32 v40, v5, v5
	v_max_f32_e32 v41, v4, v4
	v_max_f32_e32 v40, v41, v40
	v_max3_f32 v40, v40, v6, v7
	v_max3_f32 v40, v40, v8, v9
	v_max3_f32 v40, v40, v10, v11
	v_max3_f32 v40, v40, v12, v13
	v_max3_f32 v40, v40, v14, v15
	v_max3_f32 v40, v40, v16, v17
	v_max3_f32 v40, v40, v18, v19
	v_max3_f32 v40, v40, v20, v21
	v_max3_f32 v40, v40, v22, v23
	v_max3_f32 v40, v40, v24, v25
	v_max3_f32 v40, v40, v26, v27
	v_max3_f32 v40, v40, v28, v29
	v_max3_f32 v40, v40, v30, v31
	v_max3_f32 v40, v40, v32, v33
	v_max3_f32 v40, v40, v34, v35
	v_mov_b32_e32 v41, v40
	s_nop 1
	v_permlane32_swap_b32_e32 v40, v41
	v_max_f32_e32 v41, v41, v41
	v_max_f32_e32 v40, v40, v40
	v_max_f32_e32 v205, v40, v41
	s_cbranch_execnz .LBB0_493
